# gemm_small RowRes: bf16 residual row fetched right after the K loop (before the LDS reduction) instead of after it
# baseline (speedup 1.0000x reference)
.Lgsr_tail:
	s_waitcnt vmcnt(24)
	v_mfma_f32_16x16x32_bf16 v[36:39], v[82:85], v[116:119], v[36:39]
	v_mfma_f32_16x16x32_bf16 v[24:27], v[104:107], v[116:119], v[24:27]
	v_mfma_f32_16x16x32_bf16 v[20:23], v[108:111], v[116:119], v[20:23]
	v_mfma_f32_16x16x32_bf16 v[16:19], v[112:115], v[116:119], v[16:19]
	v_mfma_f32_16x16x32_bf16 v[12:15], v[82:85], v[120:123], v[12:15]
	v_mfma_f32_16x16x32_bf16 v[8:11], v[104:107], v[120:123], v[8:11]
	v_mfma_f32_16x16x32_bf16 v[4:7], v[108:111], v[120:123], v[4:7]
	v_mfma_f32_16x16x32_bf16 v[0:3], v[112:115], v[120:123], v[0:3]
	v_mfma_f32_16x16x32_bf16 v[28:31], v[82:85], v[124:127], v[28:31]
	v_mfma_f32_16x16x32_bf16 v[32:35], v[104:107], v[124:127], v[32:35]
	v_mfma_f32_16x16x32_bf16 v[40:43], v[108:111], v[124:127], v[40:43]
	v_mfma_f32_16x16x32_bf16 v[44:47], v[112:115], v[124:127], v[44:47]
	v_mfma_f32_16x16x32_bf16 v[48:51], v[82:85], v[128:131], v[48:51]
	v_mfma_f32_16x16x32_bf16 v[52:55], v[104:107], v[128:131], v[52:55]
	v_mfma_f32_16x16x32_bf16 v[56:59], v[108:111], v[128:131], v[56:59]
	v_mfma_f32_16x16x32_bf16 v[60:63], v[112:115], v[128:131], v[60:63]
	s_waitcnt vmcnt(16)
	v_mfma_f32_16x16x32_bf16 v[36:39], v[132:135], v[158:161], v[36:39]
	v_mfma_f32_16x16x32_bf16 v[24:27], v[136:139], v[158:161], v[24:27]
	v_mfma_f32_16x16x32_bf16 v[20:23], v[140:143], v[158:161], v[20:23]
	v_mfma_f32_16x16x32_bf16 v[16:19], v[144:147], v[158:161], v[16:19]
	v_mfma_f32_16x16x32_bf16 v[12:15], v[132:135], v[162:165], v[12:15]
	v_mfma_f32_16x16x32_bf16 v[8:11], v[136:139], v[162:165], v[8:11]
	v_mfma_f32_16x16x32_bf16 v[4:7], v[140:143], v[162:165], v[4:7]
	v_mfma_f32_16x16x32_bf16 v[0:3], v[144:147], v[162:165], v[0:3]
	v_mfma_f32_16x16x32_bf16 v[28:31], v[132:135], v[166:169], v[28:31]
	v_mfma_f32_16x16x32_bf16 v[32:35], v[136:139], v[166:169], v[32:35]
	v_mfma_f32_16x16x32_bf16 v[40:43], v[140:143], v[166:169], v[40:43]
	v_mfma_f32_16x16x32_bf16 v[44:47], v[144:147], v[166:169], v[44:47]
	v_mfma_f32_16x16x32_bf16 v[48:51], v[132:135], v[170:173], v[48:51]
	v_mfma_f32_16x16x32_bf16 v[52:55], v[136:139], v[170:173], v[52:55]
	v_mfma_f32_16x16x32_bf16 v[56:59], v[140:143], v[170:173], v[56:59]
	v_mfma_f32_16x16x32_bf16 v[60:63], v[144:147], v[170:173], v[60:63]
	s_waitcnt vmcnt(8)
	v_mfma_f32_16x16x32_bf16 v[36:39], v[174:177], v[202:205], v[36:39]
	v_mfma_f32_16x16x32_bf16 v[24:27], v[178:181], v[202:205], v[24:27]
	v_mfma_f32_16x16x32_bf16 v[20:23], v[194:197], v[202:205], v[20:23]
	v_mfma_f32_16x16x32_bf16 v[16:19], v[198:201], v[202:205], v[16:19]
	v_mfma_f32_16x16x32_bf16 v[12:15], v[174:177], v[206:209], v[12:15]
	v_mfma_f32_16x16x32_bf16 v[8:11], v[178:181], v[206:209], v[8:11]
	v_mfma_f32_16x16x32_bf16 v[4:7], v[194:197], v[206:209], v[4:7]
	v_mfma_f32_16x16x32_bf16 v[0:3], v[198:201], v[206:209], v[0:3]
	v_mfma_f32_16x16x32_bf16 v[28:31], v[174:177], v[210:213], v[28:31]
	v_mfma_f32_16x16x32_bf16 v[32:35], v[178:181], v[210:213], v[32:35]
	v_mfma_f32_16x16x32_bf16 v[40:43], v[194:197], v[210:213], v[40:43]
	v_mfma_f32_16x16x32_bf16 v[44:47], v[198:201], v[210:213], v[44:47]
	v_mfma_f32_16x16x32_bf16 v[48:51], v[174:177], v[214:217], v[48:51]
	v_mfma_f32_16x16x32_bf16 v[52:55], v[178:181], v[214:217], v[52:55]
	v_mfma_f32_16x16x32_bf16 v[56:59], v[194:197], v[214:217], v[56:59]
	v_mfma_f32_16x16x32_bf16 v[60:63], v[198:201], v[214:217], v[60:63]
	s_waitcnt vmcnt(0)
	v_mfma_f32_16x16x32_bf16 v[36:39], v[218:221], v[234:237], v[36:39]
	v_mfma_f32_16x16x32_bf16 v[24:27], v[222:225], v[234:237], v[24:27]
	v_mfma_f32_16x16x32_bf16 v[20:23], v[226:229], v[234:237], v[20:23]
	v_mfma_f32_16x16x32_bf16 v[16:19], v[230:233], v[234:237], v[16:19]
	v_mfma_f32_16x16x32_bf16 v[12:15], v[218:221], v[238:241], v[12:15]
	v_mfma_f32_16x16x32_bf16 v[8:11], v[222:225], v[238:241], v[8:11]
	v_mfma_f32_16x16x32_bf16 v[4:7], v[226:229], v[238:241], v[4:7]
	v_mfma_f32_16x16x32_bf16 v[0:3], v[230:233], v[238:241], v[0:3]
	v_mfma_f32_16x16x32_bf16 v[28:31], v[218:221], v[242:245], v[28:31]
	v_mfma_f32_16x16x32_bf16 v[32:35], v[222:225], v[242:245], v[32:35]
	v_mfma_f32_16x16x32_bf16 v[40:43], v[226:229], v[242:245], v[40:43]
	v_mfma_f32_16x16x32_bf16 v[44:47], v[230:233], v[242:245], v[44:47]
	v_mfma_f32_16x16x32_bf16 v[48:51], v[218:221], v[246:249], v[48:51]
	v_mfma_f32_16x16x32_bf16 v[52:55], v[222:225], v[246:249], v[52:55]
	v_mfma_f32_16x16x32_bf16 v[56:59], v[226:229], v[246:249], v[56:59]
	v_mfma_f32_16x16x32_bf16 v[60:63], v[230:233], v[246:249], v[60:63]
	s_lshl_b32 s23, s52, 2
	s_andn2_b32 s23, s23, 63
	v_or_b32_e32 v108, s23, v89
	v_add_u32_e32 v109, s22, v88
	v_add_u32_e32 v109, 0x4000, v109
	v_lshlrev_b32_e32 v109, 11, v109
	v_lshl_add_u32 v108, v108, 1, v109
	global_load_dwordx4 v[104:107], v108, s[44:45]
	s_barrier
	ds_write_b128 v102, v[36:39]
	ds_write_b128 v102, v[24:27] offset:64
	ds_write_b128 v102, v[20:23] offset:128
	ds_write_b128 v102, v[16:19] offset:192
	ds_write_b128 v102, v[12:15] offset:4352
	ds_write_b128 v102, v[8:11] offset:4416
	ds_write_b128 v102, v[4:7] offset:4480
	ds_write_b128 v102, v[0:3] offset:4544
	ds_write_b128 v102, v[28:31] offset:8704
	ds_write_b128 v102, v[32:35] offset:8768
	ds_write_b128 v102, v[40:43] offset:8832
	ds_write_b128 v102, v[44:47] offset:8896
	ds_write_b128 v103, v[48:51]
	ds_write_b128 v103, v[52:55] offset:64
	ds_write_b128 v103, v[56:59] offset:128
	ds_write_b128 v103, v[60:63] offset:192
	s_waitcnt lgkmcnt(0)
	s_barrier
	ds_read_b128 v[68:71], v90
	ds_read_b128 v[64:67], v90 offset:16
	ds_read_b128 v[60:63], v90 offset:17408
	ds_read_b128 v[56:59], v90 offset:17424
	ds_read_b128 v[52:55], v90 offset:34816
	ds_read_b128 v[48:51], v90 offset:34832
	ds_read_b128 v[44:47], v90 offset:52224
	ds_read_b128 v[40:43], v90 offset:52240
	ds_read_b128 v[36:39], v94
	ds_read_b128 v[32:35], v95
	ds_read_b128 v[28:31], v96
	ds_read_b128 v[24:27], v97
	ds_read_b128 v[20:23], v98
	ds_read_b128 v[12:15], v99
	ds_read_b128 v[4:7], v100
	ds_read_b128 v[0:3], v101
	s_lshl_b32 s23, s52, 2
	s_andn2_b32 s23, s23, 63
	v_or_b32_e32 v82, s23, v89
	s_and_b64 vcc, exec, s[12:13]
	v_ashrrev_i32_e32 v83, 31, v82
	s_cbranch_vccz .LBB0_756
	v_lshl_add_u64 v[8:9], v[82:83], 2, s[50:51]
	global_load_dwordx4 v[16:19], v[8:9], off
	s_nop 0
	global_load_dwordx4 v[8:11], v[8:9], off offset:16
	v_add_u32_e32 v72, s22, v88
	s_and_b64 vcc, exec, s[6:7]
	v_add_u32_e32 v84, 0x4000, v72
	s_cbranch_vccnz .LBB0_757

.LBB0_753:
	v_ashrrev_i32_e32 v85, 31, v84
	v_lshlrev_b64 v[86:87], 11, v[84:85]
	s_waitcnt vmcnt(1)
	v_lshl_add_u64 v[72:73], s[44:45], 0, v[86:87]
	v_lshl_add_u64 v[72:73], v[82:83], 1, v[72:73]
	s_waitcnt vmcnt(0)
	v_mov_b64_e32 v[72:73], v[104:105]
	v_mov_b64_e32 v[74:75], v[106:107]
	v_lshlrev_b32_e32 v76, 16, v72
	v_and_b32_e32 v77, 0xffff0000, v72
	v_lshlrev_b32_e32 v78, 16, v73
	v_and_b32_e32 v79, 0xffff0000, v73
	v_lshlrev_b32_e32 v72, 16, v74
	v_and_b32_e32 v73, 0xffff0000, v74
	v_lshlrev_b32_e32 v74, 16, v75
	v_and_b32_e32 v75, 0xffff0000, v75
